# MoBA qb>=5 loop shifted by 4 bytes (its 8-byte MFMA/VOP3 encodings no longer straddle 8-byte fetch boundaries); later code +8 bytes
# baseline (speedup 1.0000x reference)
.LBB0_453:
	v_mov_b32_e32 v177, v78
	ds_read_b128 v[78:81], v5
	ds_read_b128 v[82:85], v5 offset:16
	ds_read_b128 v[86:89], v5 offset:64
	ds_read_b128 v[90:93], v5 offset:80
	ds_read_b128 v[94:97], v5 offset:128
	ds_read_b128 v[98:101], v5 offset:144
	ds_read_b128 v[102:105], v5 offset:192
	ds_read_b128 v[106:109], v5 offset:208
	ds_read_b128 v[162:165], v5 offset:256
	ds_read_b128 v[166:169], v5 offset:272
	ds_read_b128 v[178:181], v5 offset:320
	ds_read_b128 v[182:185], v5 offset:336
	ds_read_b128 v[200:203], v5 offset:384
	ds_read_b128 v[204:207], v5 offset:400
	ds_read_b128 v[208:211], v5 offset:448
	ds_read_b128 v[212:215], v5 offset:464
	s_waitcnt lgkmcnt(13)
	v_mov_b32_e32 v111, v86
	v_mov_b32_e32 v86, v79
	v_mov_b32_e32 v110, v78
	v_pk_mul_f32 v[86:87], v[86:87], v[10:11]
	v_mov_b32_e32 v78, v80
	v_mov_b32_e32 v79, v88
	v_mov_b32_e32 v88, v81
	s_waitcnt lgkmcnt(12)
	v_mov_b32_e32 v81, v90
	v_mov_b32_e32 v90, v83
	v_mov_b32_e32 v83, v92
	v_mov_b32_e32 v92, v85
	s_waitcnt lgkmcnt(9)
	v_mov_b32_e32 v85, v102
	v_mov_b32_e32 v102, v95
	v_pk_fma_f32 v[86:87], v[110:111], v[8:9], v[86:87]
	v_mov_b32_e32 v80, v82
	v_mov_b32_e32 v82, v84
	v_mov_b32_e32 v84, v94
	v_pk_mul_f32 v[102:103], v[102:103], v[26:27]
	v_pk_fma_f32 v[78:79], v[78:79], v[12:13], v[86:87]
	v_mov_b32_e32 v94, v96
	v_mov_b32_e32 v95, v104
	v_mov_b32_e32 v104, v97
	s_waitcnt lgkmcnt(8)
	v_mov_b32_e32 v97, v106
	v_mov_b32_e32 v106, v99
	v_mov_b32_e32 v99, v108
	v_mov_b32_e32 v108, v101
	s_waitcnt lgkmcnt(5)
	v_mov_b32_e32 v101, v178
	v_mov_b32_e32 v178, v163
	v_pk_fma_f32 v[84:85], v[84:85], v[24:25], v[102:103]
	v_pk_fma_f32 v[78:79], v[88:89], v[14:15], v[78:79]
	v_mov_b32_e32 v96, v98
	v_mov_b32_e32 v98, v100
	v_mov_b32_e32 v100, v162
	v_pk_mul_f32 v[178:179], v[178:179], v[42:43]
	v_pk_fma_f32 v[84:85], v[94:95], v[28:29], v[84:85]
	v_pk_fma_f32 v[78:79], v[80:81], v[16:17], v[78:79]
	v_mov_b32_e32 v162, v164
	v_mov_b32_e32 v163, v180
	v_mov_b32_e32 v180, v165
	s_waitcnt lgkmcnt(4)
	v_mov_b32_e32 v165, v182
	v_mov_b32_e32 v182, v167
	v_mov_b32_e32 v167, v184
	v_mov_b32_e32 v184, v169
	s_waitcnt lgkmcnt(1)
	v_mov_b32_e32 v169, v208
	v_mov_b32_e32 v208, v201
	v_pk_fma_f32 v[100:101], v[100:101], v[40:41], v[178:179]
	v_pk_fma_f32 v[84:85], v[104:105], v[30:31], v[84:85]
	v_pk_fma_f32 v[78:79], v[90:91], v[18:19], v[78:79]
	v_mov_b32_e32 v164, v166
	v_mov_b32_e32 v166, v168
	v_mov_b32_e32 v168, v200
	v_mov_b32_e32 v200, v202
	v_mov_b32_e32 v201, v210
	v_mov_b32_e32 v210, v203
	v_mov_b32_e32 v202, v204
	s_waitcnt lgkmcnt(0)
	v_mov_b32_e32 v203, v212
	v_mov_b32_e32 v212, v205
	v_mov_b32_e32 v204, v206
	v_mov_b32_e32 v205, v214
	v_mov_b32_e32 v214, v207
	v_pk_mul_f32 v[206:207], v[208:209], v[58:59]
	v_pk_fma_f32 v[86:87], v[162:163], v[44:45], v[100:101]
	v_pk_fma_f32 v[80:81], v[96:97], v[32:33], v[84:85]
	v_pk_fma_f32 v[78:79], v[82:83], v[20:21], v[78:79]
	v_pk_fma_f32 v[102:103], v[168:169], v[56:57], v[206:207]
	v_pk_fma_f32 v[86:87], v[180:181], v[46:47], v[86:87]
	v_pk_fma_f32 v[80:81], v[106:107], v[34:35], v[80:81]
	v_pk_fma_f32 v[78:79], v[92:93], v[22:23], v[78:79]
	v_pk_fma_f32 v[94:95], v[200:201], v[60:61], v[102:103]
	v_pk_fma_f32 v[84:85], v[164:165], v[48:49], v[86:87]
	v_pk_fma_f32 v[80:81], v[98:99], v[36:37], v[80:81]
	v_add_f32_e32 v78, 0, v78
	v_pk_fma_f32 v[88:89], v[210:211], v[62:63], v[94:95]
	v_pk_fma_f32 v[84:85], v[182:183], v[50:51], v[84:85]
	v_pk_fma_f32 v[80:81], v[108:109], v[38:39], v[80:81]
	v_add_f32_e32 v78, v78, v79
	v_pk_fma_f32 v[86:87], v[202:203], v[64:65], v[88:89]
	v_pk_fma_f32 v[82:83], v[166:167], v[52:53], v[84:85]
	v_add_f32_e32 v78, v78, v80
	v_pk_fma_f32 v[86:87], v[212:213], v[66:67], v[86:87]
	v_pk_fma_f32 v[82:83], v[184:185], v[54:55], v[82:83]
	v_add_f32_e32 v78, v78, v81
	v_pk_fma_f32 v[84:85], v[204:205], v[68:69], v[86:87]
	v_add_f32_e32 v78, v78, v82
	v_pk_fma_f32 v[84:85], v[214:215], v[70:71], v[84:85]
	v_add_f32_e32 v78, v78, v83
	v_add_f32_e32 v78, v78, v84
	v_add_f32_e32 v78, v78, v85
	v_mov_b32_e32 v79, v78
	s_nop 1
	v_permlane32_swap_b32_e32 v78, v79
	v_add_f32_e32 v79, v78, v79
	v_cmp_gt_f32_e32 vcc, v79, v76
	v_mov_b32_e32 v186, s56
	v_cmp_gt_f32_e64 s[0:1], v79, v77
	v_cndmask_b32_e32 v76, v76, v79, vcc
	s_add_i32 s56, s56, 1
	v_cndmask_b32_e64 v76, v76, v77, s[0:1]
	v_cndmask_b32_e64 v77, v77, v79, s[0:1]
	v_cmp_gt_f32_e64 s[2:3], v79, v7
	v_cndmask_b32_e32 v74, v74, v186, vcc
	v_cndmask_b32_e64 v80, v75, v186, s[0:1]
	v_add_u32_e32 v5, 0x200, v5
	s_cmp_lg_u32 s93, s56
	v_cndmask_b32_e64 v74, v74, v75, s[0:1]
	v_cndmask_b32_e64 v77, v77, v7, s[2:3]
	v_cndmask_b32_e64 v78, v177, v186, s[2:3]
	v_cndmask_b32_e64 v7, v7, v79, s[2:3]
	v_cndmask_b32_e64 v75, v80, v177, s[2:3]
	s_cbranch_scc1 .LBB0_453
	v_lshlrev_b32_e64 v5, v78, 1
	v_lshlrev_b32_e64 v7, v75, 1
	v_lshlrev_b32_e64 v8, v74, 1
	v_lshl_add_u64 v[164:165], v[0:1], 1, s[52:53]
	v_lshlrev_b32_e32 v0, 1, v3
	v_or3_b32 v178, v8, v5, v7
	v_mov_b32_e32 v5, v1
	v_lshl_add_u64 v[168:169], s[52:53], 0, v[0:1]
	v_lshlrev_b32_e32 v180, 2, v72
	v_bfe_u32 v0, v2, 2, 2
	v_lshrrev_b32_e32 v3, 3, v2
	v_bfe_u32 v2, v2, 1, 1
	v_lshl_add_u64 v[162:163], s[54:55], 0, v[4:5]
	v_and_or_b32 v2, v3, 2, v2
	v_lshlrev_b32_e32 v3, 2, v0
	v_lshlrev_b32_e32 v5, 3, v174
	v_or_b32_e32 v0, v180, v0
	v_or_b32_e32 v4, v3, v72
	v_and_b32_e32 v181, 8, v5
	v_xor_b32_e32 v5, v72, v145
	v_lshlrev_b32_e32 v203, 8, v0
	v_bitop3_b32 v0, v3, v2, v72 bitop3:0x36
	v_lshlrev_b32_e32 v182, 4, v5
	v_bitop3_b32 v5, v72, v145, 2 bitop3:0x36
	v_lshlrev_b32_e32 v204, 4, v0
	v_bitop3_b32 v0, v4, v2, 2 bitop3:0x36
	v_lshlrev_b32_e32 v183, 4, v5
	v_bitop3_b32 v5, v72, v145, 4 bitop3:0x36
	v_lshlrev_b32_e32 v205, 4, v0
	v_or_b32_e32 v0, 4, v2
	v_lshlrev_b32_e32 v184, 4, v5
	v_bitop3_b32 v5, v72, v145, 6 bitop3:0x36
	v_bitop3_b32 v0, v4, v0, 2 bitop3:0x36
	v_lshlrev_b32_e32 v185, 4, v5
	v_bitop3_b32 v5, v72, v145, 8 bitop3:0x36
	v_lshlrev_b32_e32 v207, 4, v0
	v_or_b32_e32 v0, 8, v2
	v_lshlrev_b32_e32 v186, 4, v5
	v_bitop3_b32 v5, v72, v145, 10 bitop3:0x36
	v_bitop3_b32 v0, v4, v0, 2 bitop3:0x36
	v_lshlrev_b32_e32 v200, 4, v5
	v_bitop3_b32 v5, v72, v145, 12 bitop3:0x36
	v_bitop3_b32 v3, v2, v4, 4 bitop3:0x36
	v_lshlrev_b32_e32 v209, 4, v0
	v_or_b32_e32 v0, 12, v2
	v_mov_b32_e32 v7, v1
	v_lshlrev_b32_e32 v201, 4, v5
	v_bitop3_b32 v5, v72, v145, 14 bitop3:0x36
	v_lshlrev_b32_e32 v206, 4, v3
	v_bitop3_b32 v3, v2, v4, 8 bitop3:0x36
	v_bitop3_b32 v2, v2, v4, 12 bitop3:0x36
	v_bitop3_b32 v0, v4, v0, 2 bitop3:0x36
	v_mov_b32_e32 v14, v1
	v_mov_b32_e32 v15, v1
	s_lshl_b32 s56, s93, 2
	v_lshl_add_u64 v[166:167], s[54:55], 0, v[6:7]
	v_lshlrev_b32_e32 v177, 8, v73
	v_lshlrev_b32_e32 v202, 4, v5
	v_lshlrev_b32_e32 v208, 4, v3
	v_lshlrev_b32_e32 v210, 4, v2
	v_lshlrev_b32_e32 v211, 4, v0
	v_mov_b32_e32 v0, v1
	v_mov_b32_e32 v2, v1
	v_mov_b32_e32 v3, v1
	v_mov_b32_e32 v4, v1
	v_mov_b32_e32 v5, v1
	v_mov_b32_e32 v6, v1
	v_mov_b32_e32 v8, v1
	v_mov_b32_e32 v9, v1
	v_mov_b32_e32 v10, v1
	v_mov_b32_e32 v11, v1
	v_mov_b32_e32 v12, v1
	v_mov_b32_e32 v13, v1
	v_mov_b64_e32 v[30:31], v[14:15]
	v_mov_b64_e32 v[46:47], v[14:15]
	v_mov_b64_e32 v[62:63], v[14:15]
	v_mov_b64_e32 v[78:79], v[14:15]
	s_add_i32 s56, s56, 4
	s_or_b32 s54, s94, 31
	v_add_u32_e32 v179, 0, v177
	s_mov_b32 s55, 0
	v_mov_b32_e32 v212, 0
	v_mov_b32_e32 v213, 0xf149f2ca
	s_mov_b32 s57, 0
	v_mov_b64_e32 v[28:29], v[12:13]
	v_mov_b64_e32 v[26:27], v[10:11]
	v_mov_b64_e32 v[24:25], v[8:9]
	v_mov_b64_e32 v[22:23], v[6:7]
	v_mov_b64_e32 v[20:21], v[4:5]
	v_mov_b64_e32 v[18:19], v[2:3]
	v_mov_b64_e32 v[16:17], v[0:1]
	v_mov_b64_e32 v[44:45], v[12:13]
	v_mov_b64_e32 v[42:43], v[10:11]
	v_mov_b64_e32 v[40:41], v[8:9]
	v_mov_b64_e32 v[38:39], v[6:7]
	v_mov_b64_e32 v[36:37], v[4:5]
	v_mov_b64_e32 v[34:35], v[2:3]
	v_mov_b64_e32 v[32:33], v[0:1]
	v_mov_b64_e32 v[60:61], v[12:13]
	v_mov_b64_e32 v[58:59], v[10:11]
	v_mov_b64_e32 v[56:57], v[8:9]
	v_mov_b64_e32 v[54:55], v[6:7]
	v_mov_b64_e32 v[52:53], v[4:5]
	v_mov_b64_e32 v[50:51], v[2:3]
	v_mov_b64_e32 v[48:49], v[0:1]
	v_mov_b64_e32 v[76:77], v[12:13]
	v_mov_b64_e32 v[74:75], v[10:11]
	v_mov_b64_e32 v[72:73], v[8:9]
	v_mov_b64_e32 v[70:71], v[6:7]
	v_mov_b64_e32 v[68:69], v[4:5]
	v_mov_b64_e32 v[66:67], v[2:3]
	v_mov_b64_e32 v[64:65], v[0:1]
	s_mov_b32 s59, 0
	s_branch .LBB0_457
	s_nop 0

.LBB0_468:
	v_sub_f32_e32 v8, v82, v2
	v_sub_f32_e32 v9, v83, v2
	v_sub_f32_e32 v7, v98, v2
	v_exp_f32_e32 v98, v8
	v_sub_f32_e32 v8, v99, v2
	v_exp_f32_e32 v99, v9
	v_sub_f32_e32 v9, v100, v2
	v_exp_f32_e32 v12, v9
	v_sub_f32_e32 v9, v84, v2
	v_exp_f32_e32 v100, v9
	v_sub_f32_e32 v9, v101, v2
	v_exp_f32_e32 v13, v9
	v_sub_f32_e32 v9, v85, v2
	v_exp_f32_e32 v101, v9
	v_sub_f32_e32 v9, v102, v2
	v_exp_f32_e32 v14, v9
	v_sub_f32_e32 v9, v86, v2
	v_exp_f32_e32 v102, v9
	v_sub_f32_e32 v9, v103, v2
	v_exp_f32_e32 v15, v9
	v_sub_f32_e32 v9, v87, v2
	v_sub_f32_e32 v3, v96, v2
	v_sub_f32_e32 v4, v80, v2
	v_exp_f32_e32 v103, v9
	v_sub_f32_e32 v9, v104, v2
	v_exp_f32_e32 v3, v3
	v_exp_f32_e32 v96, v4
	v_sub_f32_e32 v4, v97, v2
	v_sub_f32_e32 v5, v81, v2
	v_exp_f32_e32 v104, v9
	v_sub_f32_e32 v9, v88, v2
	v_exp_f32_e32 v4, v4
	v_exp_f32_e32 v97, v5
	v_exp_f32_e32 v88, v9
	v_sub_f32_e32 v9, v105, v2
	v_exp_f32_e32 v7, v7
	v_exp_f32_e32 v105, v9
	v_sub_f32_e32 v9, v89, v2
	v_exp_f32_e32 v8, v8
	v_exp_f32_e32 v89, v9
	v_sub_f32_e32 v9, v106, v2
	v_add_f32_e32 v5, v3, v96
	v_exp_f32_e32 v106, v9
	v_sub_f32_e32 v9, v90, v2
	v_add_f32_e32 v5, 0, v5
	v_add_f32_e32 v6, v4, v97
	v_exp_f32_e32 v90, v9
	v_sub_f32_e32 v9, v107, v2
	v_add_f32_e32 v5, v6, v5
	v_add_f32_e32 v6, v7, v98
	v_exp_f32_e32 v107, v9
	v_sub_f32_e32 v9, v91, v2
	v_add_f32_e32 v5, v6, v5
	v_add_f32_e32 v6, v8, v99
	v_exp_f32_e32 v91, v9
	v_sub_f32_e32 v9, v108, v2
	v_add_f32_e32 v5, v6, v5
	v_add_f32_e32 v6, v12, v100
	v_exp_f32_e32 v108, v9
	v_sub_f32_e32 v9, v92, v2
	v_add_f32_e32 v5, v6, v5
	v_add_f32_e32 v6, v13, v101
	v_exp_f32_e32 v92, v9
	v_sub_f32_e32 v9, v109, v2
	v_add_f32_e32 v5, v6, v5
	v_add_f32_e32 v6, v14, v102
	v_exp_f32_e32 v109, v9
	v_sub_f32_e32 v9, v93, v2
	v_add_f32_e32 v5, v6, v5
	v_add_f32_e32 v6, v15, v103
	v_exp_f32_e32 v93, v9
	v_sub_f32_e32 v9, v110, v2
	v_add_f32_e32 v5, v6, v5
	v_add_f32_e32 v6, v104, v88
	v_exp_f32_e32 v110, v9
	v_sub_f32_e32 v9, v94, v2
	v_add_f32_e32 v5, v6, v5
	v_add_f32_e32 v6, v105, v89
	v_exp_f32_e32 v94, v9
	v_sub_f32_e32 v9, v111, v2
	v_add_f32_e32 v5, v6, v5
	v_add_f32_e32 v6, v106, v90
	v_exp_f32_e32 v111, v9
	v_sub_f32_e32 v9, v95, v2
	v_add_f32_e32 v5, v6, v5
	v_add_f32_e32 v6, v107, v91
	v_exp_f32_e32 v95, v9
	v_add_f32_e32 v5, v6, v5
	v_add_f32_e32 v6, v108, v92
	v_add_f32_e32 v5, v6, v5
	v_add_f32_e32 v6, v109, v93
	v_add_f32_e32 v5, v6, v5
	v_add_f32_e32 v6, v110, v94
	v_add_f32_e32 v5, v6, v5
	v_add_f32_e32 v6, v111, v95
	v_add_f32_e32 v213, v6, v5
	v_fmac_f32_e32 v213, v212, v0
	s_add_i32 s0, s2, 0
	s_setprio 0
	v_add_u32_e32 v0, s0, v181
	v_add_u32_e32 v212, s0, v203
	v_cvt_pk_bf16_f32 v4, v3, v4
	v_add3_u32 v3, v0, v204, v203
	v_add3_u32 v86, v212, v205, v181
	v_cvt_pk_bf16_f32 v5, v7, v8
	s_nop 0
	ds_read_b64_tr_b16 v[8:9], v3 offset:32768
	ds_read_b64_tr_b16 v[10:11], v86 offset:34816
	v_cvt_pk_bf16_f32 v6, v12, v13
	v_cvt_pk_bf16_f32 v7, v14, v15
	ds_read_b64_tr_b16 v[12:13], v3 offset:36864
	ds_read_b64_tr_b16 v[80:81], v3 offset:40960
	ds_read_b64_tr_b16 v[84:85], v3 offset:45056
	ds_read_b64_tr_b16 v[14:15], v86 offset:38912
	ds_read_b64_tr_b16 v[82:83], v86 offset:43008
	ds_read_b64_tr_b16 v[86:87], v86 offset:47104
	s_waitcnt lgkmcnt(6)
	v_mfma_f32_32x32x16_bf16 v[64:79], v[8:11], v[4:7], v[64:79]
	v_cvt_pk_bf16_f32 v8, v104, v105
	v_cvt_pk_bf16_f32 v9, v106, v107
	v_cvt_pk_bf16_f32 v10, v108, v109
	v_cvt_pk_bf16_f32 v11, v110, v111
	v_add3_u32 v3, v0, v206, v203
	s_waitcnt lgkmcnt(2)
	v_mfma_f32_32x32x16_bf16 v[64:79], v[12:15], v[8:11], v[64:79]
	v_cvt_pk_bf16_f32 v12, v96, v97
	v_cvt_pk_bf16_f32 v13, v98, v99
	v_cvt_pk_bf16_f32 v14, v100, v101
	v_cvt_pk_bf16_f32 v15, v102, v103
	v_add3_u32 v100, v212, v207, v181
	s_waitcnt lgkmcnt(1)
	v_mfma_f32_32x32x16_bf16 v[64:79], v[80:83], v[12:15], v[64:79]
	v_cvt_pk_bf16_f32 v80, v88, v89
	ds_read_b64_tr_b16 v[88:89], v100 offset:34816
	v_cvt_pk_bf16_f32 v81, v90, v91
	v_cvt_pk_bf16_f32 v82, v92, v93
	v_cvt_pk_bf16_f32 v83, v94, v95
	s_waitcnt lgkmcnt(1)
	s_nop 0
	v_mfma_f32_32x32x16_bf16 v[64:79], v[84:87], v[80:83], v[64:79]
	ds_read_b64_tr_b16 v[86:87], v3 offset:32768
	ds_read_b64_tr_b16 v[90:91], v3 offset:36864
	ds_read_b64_tr_b16 v[94:95], v3 offset:40960
	ds_read_b64_tr_b16 v[98:99], v3 offset:45056
	ds_read_b64_tr_b16 v[92:93], v100 offset:38912
	ds_read_b64_tr_b16 v[96:97], v100 offset:43008
	ds_read_b64_tr_b16 v[100:101], v100 offset:47104
	v_add3_u32 v3, v0, v208, v203
	v_add3_u32 v0, v0, v210, v203
	s_waitcnt lgkmcnt(6)
	v_mfma_f32_32x32x16_bf16 v[48:63], v[86:89], v[4:7], v[48:63]
	s_waitcnt lgkmcnt(2)
	v_mfma_f32_32x32x16_bf16 v[48:63], v[90:93], v[8:11], v[48:63]
	s_waitcnt lgkmcnt(1)
	v_mfma_f32_32x32x16_bf16 v[48:63], v[94:97], v[12:15], v[48:63]
	s_waitcnt lgkmcnt(0)
	v_mfma_f32_32x32x16_bf16 v[48:63], v[98:101], v[80:83], v[48:63]
	v_add3_u32 v98, v212, v209, v181
	ds_read_b64_tr_b16 v[86:87], v98 offset:34816
	ds_read_b64_tr_b16 v[84:85], v3 offset:32768
	ds_read_b64_tr_b16 v[88:89], v3 offset:36864
	ds_read_b64_tr_b16 v[92:93], v3 offset:40960
	ds_read_b64_tr_b16 v[96:97], v3 offset:45056
	ds_read_b64_tr_b16 v[90:91], v98 offset:38912
	ds_read_b64_tr_b16 v[94:95], v98 offset:43008
	ds_read_b64_tr_b16 v[98:99], v98 offset:47104
	v_add3_u32 v3, v212, v211, v181
	v_mov_b32_e32 v212, v213
	s_waitcnt lgkmcnt(6)
	v_mfma_f32_32x32x16_bf16 v[32:47], v[84:87], v[4:7], v[32:47]
	s_waitcnt lgkmcnt(2)
	v_mfma_f32_32x32x16_bf16 v[32:47], v[88:91], v[8:11], v[32:47]
	s_waitcnt lgkmcnt(1)
	v_mfma_f32_32x32x16_bf16 v[32:47], v[92:95], v[12:15], v[32:47]
	s_waitcnt lgkmcnt(0)
	v_mfma_f32_32x32x16_bf16 v[32:47], v[96:99], v[80:83], v[32:47]
	ds_read_b64_tr_b16 v[86:87], v3 offset:34816
	ds_read_b64_tr_b16 v[84:85], v0 offset:32768
	ds_read_b64_tr_b16 v[88:89], v0 offset:36864
	ds_read_b64_tr_b16 v[92:93], v0 offset:40960
	ds_read_b64_tr_b16 v[96:97], v0 offset:45056
	ds_read_b64_tr_b16 v[90:91], v3 offset:38912
	ds_read_b64_tr_b16 v[94:95], v3 offset:43008
	ds_read_b64_tr_b16 v[98:99], v3 offset:47104
	s_waitcnt lgkmcnt(6)
	v_mfma_f32_32x32x16_bf16 v[16:31], v[84:87], v[4:7], v[16:31]
	s_waitcnt lgkmcnt(2)
	v_mfma_f32_32x32x16_bf16 v[16:31], v[88:91], v[8:11], v[16:31]
	s_waitcnt lgkmcnt(1)
	v_mfma_f32_32x32x16_bf16 v[16:31], v[92:95], v[12:15], v[16:31]
	s_waitcnt lgkmcnt(0)
	v_mfma_f32_32x32x16_bf16 v[16:31], v[96:99], v[80:83], v[16:31]
	s_add_i32 s57, s57, 64
	s_addk_i32 s55, 0x4000
	s_cmp_lg_u32 s56, s58
	s_cbranch_scc1 .LBB0_456
	s_branch .LBB0_262
	s_nop 0
